# GU and Down K-loops: leading half-workgroup skips the lgkmcnt(0) before barrier 1 (its LDS slots are restaged two barriers later; the post-barrier wait still guards the MFMAs)
# speedup vs baseline: 1.0022x; 1.0022x over previous
.Lzgo_1:
	s_add_u32 s22, s22, 0x80
	s_addc_u32 s23, s23, 0
	s_add_u32 vcc_lo, s66, 0x100
	s_addc_u32 vcc_hi, s67, 0
	s_mov_b32 s66, 0
	s_add_i32 s88, s66, 2
	s_add_u32 s62, s22, 0x80
	s_addc_u32 s63, s23, 0
	s_add_i32 s89, 0, 0x10000
	s_cmp_eq_u32 s93, s66
	s_cselect_b32 s67, s3, s63
	s_cselect_b32 s66, s2, s62
	v_add_u32_e32 v149, s89, v146
	s_cselect_b32 s63, s21, vcc_hi
	s_cselect_b32 s62, s20, vcc_lo
	s_add_i32 s31, 0, 0x14000
	ds_read_b128 v[142:145], v149
	ds_read_b128 v[150:153], v149 offset:1024
	ds_read_b128 v[154:157], v149 offset:2048
	ds_read_b128 v[158:161], v149 offset:3072
	v_add_u32_e32 v149, s31, v146
	ds_read_b128 v[162:165], v149
	ds_read_b128 v[166:169], v149 offset:1024
	ds_read_b128 v[170:173], v149 offset:2048
	ds_read_b128 v[174:177], v149 offset:3072
	v_lshl_add_u64 v[218:219], s[22:23], 0, v[138:139]
	s_add_i32 m0, s77, 0xc000
	ds_read_b128 v[178:181], v148
	ds_read_b128 v[182:185], v148 offset:1024
	ds_read_b128 v[186:189], v148 offset:2048
	ds_read_b128 v[190:193], v148 offset:3072
	ds_read_b128 v[194:197], v148 offset:4096
	ds_read_b128 v[198:201], v148 offset:5120
	ds_read_b128 v[202:205], v148 offset:6144
	ds_read_b128 v[214:217], v148 offset:7168
	global_load_lds_dwordx4 v[218:219], off
	v_lshl_add_u64 v[218:219], s[22:23], 0, v[140:141]
	s_add_i32 m0, s77, 0xe000
	s_nop 0
	global_load_lds_dwordx4 v[218:219], off
	s_waitcnt vmcnt(8)
	s_cmp_lg_u64 s[18:19], 0
	s_cbranch_scc1 .Lrwp_g0k
	s_waitcnt lgkmcnt(0)
.Lrwp_g0k:
	s_barrier
	s_setprio 1
	s_waitcnt lgkmcnt(0)
	v_mfma_f32_16x16x32_bf16 v[122:125], v[142:145], v[178:181], 0
	v_mfma_f32_16x16x32_bf16 v[118:121], v[154:157], v[178:181], 0
	v_mfma_f32_16x16x32_bf16 v[110:113], v[142:145], v[186:189], 0
	v_mfma_f32_16x16x32_bf16 v[102:105], v[154:157], v[186:189], 0
	v_mfma_f32_16x16x32_bf16 v[94:97], v[142:145], v[194:197], 0
	v_mfma_f32_16x16x32_bf16 v[86:89], v[154:157], v[194:197], 0
	v_mfma_f32_16x16x32_bf16 v[78:81], v[142:145], v[202:205], 0
	v_mfma_f32_16x16x32_bf16 v[70:73], v[154:157], v[202:205], 0
	v_mfma_f32_16x16x32_bf16 v[122:125], v[150:153], v[182:185], v[122:125]
	v_mfma_f32_16x16x32_bf16 v[118:121], v[158:161], v[182:185], v[118:121]
	v_mfma_f32_16x16x32_bf16 v[110:113], v[150:153], v[190:193], v[110:113]
	v_mfma_f32_16x16x32_bf16 v[102:105], v[158:161], v[190:193], v[102:105]
	v_mfma_f32_16x16x32_bf16 v[94:97], v[150:153], v[198:201], v[94:97]
	v_mfma_f32_16x16x32_bf16 v[86:89], v[158:161], v[198:201], v[86:89]
	v_mfma_f32_16x16x32_bf16 v[78:81], v[150:153], v[214:217], v[78:81]
	v_mfma_f32_16x16x32_bf16 v[70:73], v[158:161], v[214:217], v[70:73]
	s_setprio 0
	s_setprio 1
	v_mfma_f32_16x16x32_bf16 v[126:129], v[162:165], v[178:181], 0
	v_mfma_f32_16x16x32_bf16 v[114:117], v[170:173], v[178:181], 0
	v_mfma_f32_16x16x32_bf16 v[106:109], v[162:165], v[186:189], 0
	v_mfma_f32_16x16x32_bf16 v[98:101], v[170:173], v[186:189], 0
	v_mfma_f32_16x16x32_bf16 v[90:93], v[162:165], v[194:197], 0
	v_mfma_f32_16x16x32_bf16 v[82:85], v[170:173], v[194:197], 0
	v_mfma_f32_16x16x32_bf16 v[74:77], v[162:165], v[202:205], 0
	v_mfma_f32_16x16x32_bf16 v[66:69], v[170:173], v[202:205], 0
	v_mfma_f32_16x16x32_bf16 v[126:129], v[166:169], v[182:185], v[126:129]
	v_mfma_f32_16x16x32_bf16 v[114:117], v[174:177], v[182:185], v[114:117]
	v_mfma_f32_16x16x32_bf16 v[106:109], v[166:169], v[190:193], v[106:109]
	v_mfma_f32_16x16x32_bf16 v[98:101], v[174:177], v[190:193], v[98:101]
	v_mfma_f32_16x16x32_bf16 v[90:93], v[166:169], v[198:201], v[90:93]
	v_mfma_f32_16x16x32_bf16 v[82:85], v[174:177], v[198:201], v[82:85]
	v_mfma_f32_16x16x32_bf16 v[74:77], v[166:169], v[214:217], v[74:77]
	v_mfma_f32_16x16x32_bf16 v[66:69], v[174:177], v[214:217], v[66:69]
	s_setprio 0
	s_barrier
	s_add_i32 s89, s89, s74
	v_lshl_add_u64 v[218:219], s[62:63], 0, v[134:135]
	s_mov_b32 m0, s89
	ds_read_b128 v[178:181], v148 offset:16384
	ds_read_b128 v[182:185], v148 offset:17408
	ds_read_b128 v[186:189], v148 offset:18432
	ds_read_b128 v[190:193], v148 offset:19456
	ds_read_b128 v[194:197], v148 offset:20480
	ds_read_b128 v[198:201], v148 offset:21504
	ds_read_b128 v[202:205], v148 offset:22528
	ds_read_b128 v[214:217], v148 offset:23552
	global_load_lds_dwordx4 v[218:219], off
	s_add_i32 m0, s89, 0x2000
	v_lshl_add_u64 v[220:221], s[62:63], 0, v[130:131]
	s_add_u32 s62, s62, s8
	s_addc_u32 s63, s63, s9
	s_add_i32 s31, s31, s74
	global_load_lds_dwordx4 v[220:221], off
	v_lshl_add_u64 v[222:223], s[62:63], 0, v[134:135]
	s_mov_b32 m0, s31
	v_lshl_add_u64 v[224:225], s[62:63], 0, v[130:131]
	global_load_lds_dwordx4 v[222:223], off
	s_add_i32 m0, s31, 0x2000
	v_lshl_add_u64 v[226:227], s[66:67], 0, v[136:137]
	global_load_lds_dwordx4 v[224:225], off
	s_mov_b32 m0, s77
	v_lshl_add_u64 v[236:237], s[66:67], 0, v[132:133]
	global_load_lds_dwordx4 v[226:227], off
	s_mov_b32 m0, s78
	s_nop 0
	global_load_lds_dwordx4 v[236:237], off
	s_waitcnt vmcnt(8)
	s_cmp_lg_u64 s[18:19], 0
	s_cbranch_scc1 .Lrwp_g1k
	s_waitcnt lgkmcnt(0)
.Lrwp_g1k:
	s_barrier
	s_setprio 1
	s_waitcnt lgkmcnt(0)
	v_mfma_f32_16x16x32_bf16 v[62:65], v[142:145], v[178:181], 0
	v_mfma_f32_16x16x32_bf16 v[54:57], v[154:157], v[178:181], 0
	v_mfma_f32_16x16x32_bf16 v[46:49], v[142:145], v[186:189], 0
	v_mfma_f32_16x16x32_bf16 v[38:41], v[154:157], v[186:189], 0
	v_mfma_f32_16x16x32_bf16 v[30:33], v[142:145], v[194:197], 0
	v_mfma_f32_16x16x32_bf16 v[22:25], v[154:157], v[194:197], 0
	v_mfma_f32_16x16x32_bf16 v[14:17], v[142:145], v[202:205], 0
	v_mfma_f32_16x16x32_bf16 v[6:9], v[154:157], v[202:205], 0
	v_mfma_f32_16x16x32_bf16 v[62:65], v[150:153], v[182:185], v[62:65]
	v_mfma_f32_16x16x32_bf16 v[54:57], v[158:161], v[182:185], v[54:57]
	v_mfma_f32_16x16x32_bf16 v[46:49], v[150:153], v[190:193], v[46:49]
	v_mfma_f32_16x16x32_bf16 v[38:41], v[158:161], v[190:193], v[38:41]
	v_mfma_f32_16x16x32_bf16 v[30:33], v[150:153], v[198:201], v[30:33]
	v_mfma_f32_16x16x32_bf16 v[22:25], v[158:161], v[198:201], v[22:25]
	v_mfma_f32_16x16x32_bf16 v[14:17], v[150:153], v[214:217], v[14:17]
	v_mfma_f32_16x16x32_bf16 v[6:9], v[158:161], v[214:217], v[6:9]
	s_setprio 0
	s_setprio 1
	v_mfma_f32_16x16x32_bf16 v[58:61], v[162:165], v[178:181], 0
	v_mfma_f32_16x16x32_bf16 v[50:53], v[170:173], v[178:181], 0
	v_mfma_f32_16x16x32_bf16 v[42:45], v[162:165], v[186:189], 0
	v_mfma_f32_16x16x32_bf16 v[34:37], v[170:173], v[186:189], 0
	v_mfma_f32_16x16x32_bf16 v[26:29], v[162:165], v[194:197], 0
	v_mfma_f32_16x16x32_bf16 v[18:21], v[170:173], v[194:197], 0
	v_mfma_f32_16x16x32_bf16 v[10:13], v[162:165], v[202:205], 0
	v_mfma_f32_16x16x32_bf16 v[2:5], v[170:173], v[202:205], 0
	v_mfma_f32_16x16x32_bf16 v[58:61], v[166:169], v[182:185], v[58:61]
	v_mfma_f32_16x16x32_bf16 v[50:53], v[174:177], v[182:185], v[50:53]
	v_mfma_f32_16x16x32_bf16 v[42:45], v[166:169], v[190:193], v[42:45]
	v_mfma_f32_16x16x32_bf16 v[34:37], v[174:177], v[190:193], v[34:37]
	v_mfma_f32_16x16x32_bf16 v[26:29], v[166:169], v[198:201], v[26:29]
	v_mfma_f32_16x16x32_bf16 v[18:21], v[174:177], v[198:201], v[18:21]
	v_mfma_f32_16x16x32_bf16 v[10:13], v[166:169], v[214:217], v[10:13]
	v_mfma_f32_16x16x32_bf16 v[2:5], v[174:177], v[214:217], v[2:5]
	s_setprio 0
	s_barrier
	s_add_i32 s31, 0, 0x18000
	v_add_u32_e32 v149, s31, v146
	s_add_i32 s89, 0, 0x1c000
	ds_read_b128 v[142:145], v149
	ds_read_b128 v[150:153], v149 offset:1024
	ds_read_b128 v[154:157], v149 offset:2048
	ds_read_b128 v[158:161], v149 offset:3072
	v_add_u32_e32 v149, s89, v146
	ds_read_b128 v[162:165], v149
	ds_read_b128 v[166:169], v149 offset:1024
	ds_read_b128 v[170:173], v149 offset:2048
	ds_read_b128 v[174:177], v149 offset:3072
	s_add_u32 s62, s66, s8
	s_addc_u32 s63, s67, s9
	s_mov_b32 m0, s79
	v_lshl_add_u64 v[238:239], s[62:63], 0, v[136:137]
	ds_read_b128 v[178:181], v148 offset:32768
	ds_read_b128 v[182:185], v148 offset:33792
	ds_read_b128 v[186:189], v148 offset:34816
	ds_read_b128 v[190:193], v148 offset:35840
	ds_read_b128 v[194:197], v148 offset:36864
	ds_read_b128 v[198:201], v148 offset:37888
	ds_read_b128 v[202:205], v148 offset:38912
	ds_read_b128 v[214:217], v148 offset:39936
	global_load_lds_dwordx4 v[238:239], off
	v_lshl_add_u64 v[238:239], s[62:63], 0, v[132:133]
	s_mov_b32 m0, s90
	s_nop 0
	global_load_lds_dwordx4 v[238:239], off
	s_waitcnt vmcnt(8)
	s_cmp_lg_u64 s[18:19], 0
	s_cbranch_scc1 .Lrwp_g2k
	s_waitcnt lgkmcnt(0)
.Lrwp_g2k:
	s_barrier
	s_setprio 1
	s_waitcnt lgkmcnt(0)
	v_mfma_f32_16x16x32_bf16 v[122:125], v[142:145], v[178:181], v[122:125]
	v_mfma_f32_16x16x32_bf16 v[118:121], v[154:157], v[178:181], v[118:121]
	v_mfma_f32_16x16x32_bf16 v[110:113], v[142:145], v[186:189], v[110:113]
	v_mfma_f32_16x16x32_bf16 v[102:105], v[154:157], v[186:189], v[102:105]
	v_mfma_f32_16x16x32_bf16 v[94:97], v[142:145], v[194:197], v[94:97]
	v_mfma_f32_16x16x32_bf16 v[86:89], v[154:157], v[194:197], v[86:89]
	v_mfma_f32_16x16x32_bf16 v[78:81], v[142:145], v[202:205], v[78:81]
	v_mfma_f32_16x16x32_bf16 v[70:73], v[154:157], v[202:205], v[70:73]
	v_mfma_f32_16x16x32_bf16 v[122:125], v[150:153], v[182:185], v[122:125]
	v_mfma_f32_16x16x32_bf16 v[118:121], v[158:161], v[182:185], v[118:121]
	v_mfma_f32_16x16x32_bf16 v[110:113], v[150:153], v[190:193], v[110:113]
	v_mfma_f32_16x16x32_bf16 v[102:105], v[158:161], v[190:193], v[102:105]
	v_mfma_f32_16x16x32_bf16 v[94:97], v[150:153], v[198:201], v[94:97]
	v_mfma_f32_16x16x32_bf16 v[86:89], v[158:161], v[198:201], v[86:89]
	v_mfma_f32_16x16x32_bf16 v[78:81], v[150:153], v[214:217], v[78:81]
	v_mfma_f32_16x16x32_bf16 v[70:73], v[158:161], v[214:217], v[70:73]
	s_setprio 0
	s_setprio 1
	v_mfma_f32_16x16x32_bf16 v[126:129], v[162:165], v[178:181], v[126:129]
	v_mfma_f32_16x16x32_bf16 v[114:117], v[170:173], v[178:181], v[114:117]
	v_mfma_f32_16x16x32_bf16 v[106:109], v[162:165], v[186:189], v[106:109]
	v_mfma_f32_16x16x32_bf16 v[98:101], v[170:173], v[186:189], v[98:101]
	v_mfma_f32_16x16x32_bf16 v[90:93], v[162:165], v[194:197], v[90:93]
	v_mfma_f32_16x16x32_bf16 v[82:85], v[170:173], v[194:197], v[82:85]
	v_mfma_f32_16x16x32_bf16 v[74:77], v[162:165], v[202:205], v[74:77]
	v_mfma_f32_16x16x32_bf16 v[66:69], v[170:173], v[202:205], v[66:69]
	v_mfma_f32_16x16x32_bf16 v[126:129], v[166:169], v[182:185], v[126:129]
	v_mfma_f32_16x16x32_bf16 v[114:117], v[174:177], v[182:185], v[114:117]
	v_mfma_f32_16x16x32_bf16 v[106:109], v[166:169], v[190:193], v[106:109]
	v_mfma_f32_16x16x32_bf16 v[98:101], v[174:177], v[190:193], v[98:101]
	v_mfma_f32_16x16x32_bf16 v[90:93], v[166:169], v[198:201], v[90:93]
	v_mfma_f32_16x16x32_bf16 v[82:85], v[174:177], v[198:201], v[82:85]
	v_mfma_f32_16x16x32_bf16 v[74:77], v[166:169], v[214:217], v[74:77]
	v_mfma_f32_16x16x32_bf16 v[66:69], v[174:177], v[214:217], v[66:69]
	s_setprio 0
	s_barrier
	s_add_i32 s31, s31, s74
	v_lshl_add_u64 v[218:219], v[218:219], 0, s[60:61]
	s_mov_b32 m0, s31
	ds_read_b128 v[178:181], v148 offset:49152
	ds_read_b128 v[182:185], v148 offset:50176
	ds_read_b128 v[186:189], v148 offset:51200
	ds_read_b128 v[190:193], v148 offset:52224
	ds_read_b128 v[194:197], v148 offset:53248
	ds_read_b128 v[198:201], v148 offset:54272
	ds_read_b128 v[202:205], v148 offset:55296
	ds_read_b128 v[214:217], v148 offset:56320
	global_load_lds_dwordx4 v[218:219], off
	v_lshl_add_u64 v[218:219], v[220:221], 0, s[60:61]
	s_add_i32 m0, s31, 0x2000
	s_add_i32 s31, s89, s74
	global_load_lds_dwordx4 v[218:219], off
	v_lshl_add_u64 v[218:219], v[222:223], 0, s[60:61]
	s_mov_b32 m0, s31
	s_nop 0
	global_load_lds_dwordx4 v[218:219], off
	v_lshl_add_u64 v[218:219], v[224:225], 0, s[60:61]
	s_add_i32 m0, s31, 0x2000
	s_nop 0
	global_load_lds_dwordx4 v[218:219], off
	v_lshl_add_u64 v[218:219], v[226:227], 0, s[60:61]
	s_mov_b32 m0, s91
	s_nop 0
	global_load_lds_dwordx4 v[218:219], off
	v_lshl_add_u64 v[218:219], v[236:237], 0, s[60:61]
	s_mov_b32 m0, s92
	s_nop 0
	global_load_lds_dwordx4 v[218:219], off
	s_waitcnt vmcnt(8)
	s_cmp_lg_u64 s[18:19], 0
	s_cbranch_scc1 .Lrwp_g3k
	s_waitcnt lgkmcnt(0)
.Lrwp_g3k:
	s_barrier
	s_setprio 1
	s_waitcnt lgkmcnt(0)
	v_mfma_f32_16x16x32_bf16 v[62:65], v[142:145], v[178:181], v[62:65]
	v_mfma_f32_16x16x32_bf16 v[54:57], v[154:157], v[178:181], v[54:57]
	v_mfma_f32_16x16x32_bf16 v[46:49], v[142:145], v[186:189], v[46:49]
	v_mfma_f32_16x16x32_bf16 v[38:41], v[154:157], v[186:189], v[38:41]
	v_mfma_f32_16x16x32_bf16 v[30:33], v[142:145], v[194:197], v[30:33]
	v_mfma_f32_16x16x32_bf16 v[22:25], v[154:157], v[194:197], v[22:25]
	v_mfma_f32_16x16x32_bf16 v[14:17], v[142:145], v[202:205], v[14:17]
	v_mfma_f32_16x16x32_bf16 v[6:9], v[154:157], v[202:205], v[6:9]
	v_mfma_f32_16x16x32_bf16 v[62:65], v[150:153], v[182:185], v[62:65]
	v_mfma_f32_16x16x32_bf16 v[54:57], v[158:161], v[182:185], v[54:57]
	v_mfma_f32_16x16x32_bf16 v[46:49], v[150:153], v[190:193], v[46:49]
	v_mfma_f32_16x16x32_bf16 v[38:41], v[158:161], v[190:193], v[38:41]
	v_mfma_f32_16x16x32_bf16 v[30:33], v[150:153], v[198:201], v[30:33]
	v_mfma_f32_16x16x32_bf16 v[22:25], v[158:161], v[198:201], v[22:25]
	v_mfma_f32_16x16x32_bf16 v[14:17], v[150:153], v[214:217], v[14:17]
	v_mfma_f32_16x16x32_bf16 v[6:9], v[158:161], v[214:217], v[6:9]
	s_setprio 0
	s_setprio 1
	v_mfma_f32_16x16x32_bf16 v[58:61], v[162:165], v[178:181], v[58:61]
	v_mfma_f32_16x16x32_bf16 v[50:53], v[170:173], v[178:181], v[50:53]
	v_mfma_f32_16x16x32_bf16 v[42:45], v[162:165], v[186:189], v[42:45]
	v_mfma_f32_16x16x32_bf16 v[34:37], v[170:173], v[186:189], v[34:37]
	v_mfma_f32_16x16x32_bf16 v[26:29], v[162:165], v[194:197], v[26:29]
	v_mfma_f32_16x16x32_bf16 v[18:21], v[170:173], v[194:197], v[18:21]
	v_mfma_f32_16x16x32_bf16 v[10:13], v[162:165], v[202:205], v[10:13]
	v_mfma_f32_16x16x32_bf16 v[2:5], v[170:173], v[202:205], v[2:5]
	v_mfma_f32_16x16x32_bf16 v[58:61], v[166:169], v[182:185], v[58:61]
	v_mfma_f32_16x16x32_bf16 v[50:53], v[174:177], v[182:185], v[50:53]
	v_mfma_f32_16x16x32_bf16 v[42:45], v[166:169], v[190:193], v[42:45]
	v_mfma_f32_16x16x32_bf16 v[34:37], v[174:177], v[190:193], v[34:37]
	v_mfma_f32_16x16x32_bf16 v[26:29], v[166:169], v[198:201], v[26:29]
	v_mfma_f32_16x16x32_bf16 v[18:21], v[174:177], v[198:201], v[18:21]
	v_mfma_f32_16x16x32_bf16 v[10:13], v[166:169], v[214:217], v[10:13]
	v_mfma_f32_16x16x32_bf16 v[2:5], v[174:177], v[214:217], v[2:5]
	s_setprio 0
	s_barrier
	s_add_u32 s22, s22, 0x100
	s_addc_u32 s23, s23, 0
	s_add_u32 vcc_lo, vcc_lo, 0x100
	s_addc_u32 vcc_hi, vcc_hi, 0
	s_cmp_ge_i32 s88, s52
	s_mov_b32 s66, s88
	s_cbranch_scc1 .LBB0_288
.LBB0_287:
	s_add_i32 s88, s66, 2
	s_add_u32 s62, s22, 0x80
	s_addc_u32 s63, s23, 0
	s_add_i32 s89, 0, 0x10000
	s_cmp_eq_u32 s93, s66
	s_cselect_b32 s67, s3, s63
	s_cselect_b32 s66, s2, s62
	v_add_u32_e32 v149, s89, v146
	s_cselect_b32 s63, s21, vcc_hi
	s_cselect_b32 s62, s20, vcc_lo
	s_add_i32 s31, 0, 0x14000
	ds_read_b128 v[142:145], v149
	ds_read_b128 v[150:153], v149 offset:1024
	ds_read_b128 v[154:157], v149 offset:2048
	ds_read_b128 v[158:161], v149 offset:3072
	v_add_u32_e32 v149, s31, v146
	ds_read_b128 v[162:165], v149
	ds_read_b128 v[166:169], v149 offset:1024
	ds_read_b128 v[170:173], v149 offset:2048
	ds_read_b128 v[174:177], v149 offset:3072
	v_lshl_add_u64 v[218:219], s[22:23], 0, v[138:139]
	s_add_i32 m0, s77, 0xc000
	ds_read_b128 v[178:181], v148
	ds_read_b128 v[182:185], v148 offset:1024
	ds_read_b128 v[186:189], v148 offset:2048
	ds_read_b128 v[190:193], v148 offset:3072
	ds_read_b128 v[194:197], v148 offset:4096
	ds_read_b128 v[198:201], v148 offset:5120
	ds_read_b128 v[202:205], v148 offset:6144
	ds_read_b128 v[214:217], v148 offset:7168
	global_load_lds_dwordx4 v[218:219], off
	v_lshl_add_u64 v[218:219], s[22:23], 0, v[140:141]
	s_add_i32 m0, s77, 0xe000
	s_nop 0
	global_load_lds_dwordx4 v[218:219], off
	s_waitcnt vmcnt(8)
	s_cmp_lg_u64 s[18:19], 0
	s_cbranch_scc1 .Lrw_g0k
	s_waitcnt lgkmcnt(0)
.Lrw_g0k:
	s_barrier
	s_setprio 1
	s_waitcnt lgkmcnt(0)
	v_mfma_f32_16x16x32_bf16 v[122:125], v[142:145], v[178:181], v[122:125]
	v_mfma_f32_16x16x32_bf16 v[118:121], v[154:157], v[178:181], v[118:121]
	v_mfma_f32_16x16x32_bf16 v[110:113], v[142:145], v[186:189], v[110:113]
	v_mfma_f32_16x16x32_bf16 v[102:105], v[154:157], v[186:189], v[102:105]
	v_mfma_f32_16x16x32_bf16 v[94:97], v[142:145], v[194:197], v[94:97]
	v_mfma_f32_16x16x32_bf16 v[86:89], v[154:157], v[194:197], v[86:89]
	v_mfma_f32_16x16x32_bf16 v[78:81], v[142:145], v[202:205], v[78:81]
	v_mfma_f32_16x16x32_bf16 v[70:73], v[154:157], v[202:205], v[70:73]
	v_mfma_f32_16x16x32_bf16 v[122:125], v[150:153], v[182:185], v[122:125]
	v_mfma_f32_16x16x32_bf16 v[118:121], v[158:161], v[182:185], v[118:121]
	v_mfma_f32_16x16x32_bf16 v[110:113], v[150:153], v[190:193], v[110:113]
	v_mfma_f32_16x16x32_bf16 v[102:105], v[158:161], v[190:193], v[102:105]
	v_mfma_f32_16x16x32_bf16 v[94:97], v[150:153], v[198:201], v[94:97]
	v_mfma_f32_16x16x32_bf16 v[86:89], v[158:161], v[198:201], v[86:89]
	v_mfma_f32_16x16x32_bf16 v[78:81], v[150:153], v[214:217], v[78:81]
	v_mfma_f32_16x16x32_bf16 v[70:73], v[158:161], v[214:217], v[70:73]
	s_setprio 0
	s_setprio 1
	v_mfma_f32_16x16x32_bf16 v[126:129], v[162:165], v[178:181], v[126:129]
	v_mfma_f32_16x16x32_bf16 v[114:117], v[170:173], v[178:181], v[114:117]
	v_mfma_f32_16x16x32_bf16 v[106:109], v[162:165], v[186:189], v[106:109]
	v_mfma_f32_16x16x32_bf16 v[98:101], v[170:173], v[186:189], v[98:101]
	v_mfma_f32_16x16x32_bf16 v[90:93], v[162:165], v[194:197], v[90:93]
	v_mfma_f32_16x16x32_bf16 v[82:85], v[170:173], v[194:197], v[82:85]
	v_mfma_f32_16x16x32_bf16 v[74:77], v[162:165], v[202:205], v[74:77]
	v_mfma_f32_16x16x32_bf16 v[66:69], v[170:173], v[202:205], v[66:69]
	v_mfma_f32_16x16x32_bf16 v[126:129], v[166:169], v[182:185], v[126:129]
	v_mfma_f32_16x16x32_bf16 v[114:117], v[174:177], v[182:185], v[114:117]
	v_mfma_f32_16x16x32_bf16 v[106:109], v[166:169], v[190:193], v[106:109]
	v_mfma_f32_16x16x32_bf16 v[98:101], v[174:177], v[190:193], v[98:101]
	v_mfma_f32_16x16x32_bf16 v[90:93], v[166:169], v[198:201], v[90:93]
	v_mfma_f32_16x16x32_bf16 v[82:85], v[174:177], v[198:201], v[82:85]
	v_mfma_f32_16x16x32_bf16 v[74:77], v[166:169], v[214:217], v[74:77]
	v_mfma_f32_16x16x32_bf16 v[66:69], v[174:177], v[214:217], v[66:69]
	s_setprio 0
	s_barrier
	s_add_i32 s89, s89, s74
	v_lshl_add_u64 v[218:219], s[62:63], 0, v[134:135]
	s_mov_b32 m0, s89
	ds_read_b128 v[178:181], v148 offset:16384
	ds_read_b128 v[182:185], v148 offset:17408
	ds_read_b128 v[186:189], v148 offset:18432
	ds_read_b128 v[190:193], v148 offset:19456
	ds_read_b128 v[194:197], v148 offset:20480
	ds_read_b128 v[198:201], v148 offset:21504
	ds_read_b128 v[202:205], v148 offset:22528
	ds_read_b128 v[214:217], v148 offset:23552
	global_load_lds_dwordx4 v[218:219], off
	s_add_i32 m0, s89, 0x2000
	v_lshl_add_u64 v[220:221], s[62:63], 0, v[130:131]
	s_add_u32 s62, s62, s8
	s_addc_u32 s63, s63, s9
	s_add_i32 s31, s31, s74
	global_load_lds_dwordx4 v[220:221], off
	v_lshl_add_u64 v[222:223], s[62:63], 0, v[134:135]
	s_mov_b32 m0, s31
	v_lshl_add_u64 v[224:225], s[62:63], 0, v[130:131]
	global_load_lds_dwordx4 v[222:223], off
	s_add_i32 m0, s31, 0x2000
	v_lshl_add_u64 v[226:227], s[66:67], 0, v[136:137]
	global_load_lds_dwordx4 v[224:225], off
	s_mov_b32 m0, s77
	v_lshl_add_u64 v[236:237], s[66:67], 0, v[132:133]
	global_load_lds_dwordx4 v[226:227], off
	s_mov_b32 m0, s78
	s_nop 0
	global_load_lds_dwordx4 v[236:237], off
	s_waitcnt vmcnt(8)
	s_cmp_lg_u64 s[18:19], 0
	s_cbranch_scc1 .Lrw_g1k
	s_waitcnt lgkmcnt(0)
.Lrw_g1k:
	s_barrier
	s_setprio 1
	s_waitcnt lgkmcnt(0)
	v_mfma_f32_16x16x32_bf16 v[62:65], v[142:145], v[178:181], v[62:65]
	v_mfma_f32_16x16x32_bf16 v[54:57], v[154:157], v[178:181], v[54:57]
	v_mfma_f32_16x16x32_bf16 v[46:49], v[142:145], v[186:189], v[46:49]
	v_mfma_f32_16x16x32_bf16 v[38:41], v[154:157], v[186:189], v[38:41]
	v_mfma_f32_16x16x32_bf16 v[30:33], v[142:145], v[194:197], v[30:33]
	v_mfma_f32_16x16x32_bf16 v[22:25], v[154:157], v[194:197], v[22:25]
	v_mfma_f32_16x16x32_bf16 v[14:17], v[142:145], v[202:205], v[14:17]
	v_mfma_f32_16x16x32_bf16 v[6:9], v[154:157], v[202:205], v[6:9]
	v_mfma_f32_16x16x32_bf16 v[62:65], v[150:153], v[182:185], v[62:65]
	v_mfma_f32_16x16x32_bf16 v[54:57], v[158:161], v[182:185], v[54:57]
	v_mfma_f32_16x16x32_bf16 v[46:49], v[150:153], v[190:193], v[46:49]
	v_mfma_f32_16x16x32_bf16 v[38:41], v[158:161], v[190:193], v[38:41]
	v_mfma_f32_16x16x32_bf16 v[30:33], v[150:153], v[198:201], v[30:33]
	v_mfma_f32_16x16x32_bf16 v[22:25], v[158:161], v[198:201], v[22:25]
	v_mfma_f32_16x16x32_bf16 v[14:17], v[150:153], v[214:217], v[14:17]
	v_mfma_f32_16x16x32_bf16 v[6:9], v[158:161], v[214:217], v[6:9]
	s_setprio 0
	s_setprio 1
	v_mfma_f32_16x16x32_bf16 v[58:61], v[162:165], v[178:181], v[58:61]
	v_mfma_f32_16x16x32_bf16 v[50:53], v[170:173], v[178:181], v[50:53]
	v_mfma_f32_16x16x32_bf16 v[42:45], v[162:165], v[186:189], v[42:45]
	v_mfma_f32_16x16x32_bf16 v[34:37], v[170:173], v[186:189], v[34:37]
	v_mfma_f32_16x16x32_bf16 v[26:29], v[162:165], v[194:197], v[26:29]
	v_mfma_f32_16x16x32_bf16 v[18:21], v[170:173], v[194:197], v[18:21]
	v_mfma_f32_16x16x32_bf16 v[10:13], v[162:165], v[202:205], v[10:13]
	v_mfma_f32_16x16x32_bf16 v[2:5], v[170:173], v[202:205], v[2:5]
	v_mfma_f32_16x16x32_bf16 v[58:61], v[166:169], v[182:185], v[58:61]
	v_mfma_f32_16x16x32_bf16 v[50:53], v[174:177], v[182:185], v[50:53]
	v_mfma_f32_16x16x32_bf16 v[42:45], v[166:169], v[190:193], v[42:45]
	v_mfma_f32_16x16x32_bf16 v[34:37], v[174:177], v[190:193], v[34:37]
	v_mfma_f32_16x16x32_bf16 v[26:29], v[166:169], v[198:201], v[26:29]
	v_mfma_f32_16x16x32_bf16 v[18:21], v[174:177], v[198:201], v[18:21]
	v_mfma_f32_16x16x32_bf16 v[10:13], v[166:169], v[214:217], v[10:13]
	v_mfma_f32_16x16x32_bf16 v[2:5], v[174:177], v[214:217], v[2:5]
	s_setprio 0
	s_barrier
	s_add_i32 s31, 0, 0x18000
	v_add_u32_e32 v149, s31, v146
	s_add_i32 s89, 0, 0x1c000
	ds_read_b128 v[142:145], v149
	ds_read_b128 v[150:153], v149 offset:1024
	ds_read_b128 v[154:157], v149 offset:2048
	ds_read_b128 v[158:161], v149 offset:3072
	v_add_u32_e32 v149, s89, v146
	ds_read_b128 v[162:165], v149
	ds_read_b128 v[166:169], v149 offset:1024
	ds_read_b128 v[170:173], v149 offset:2048
	ds_read_b128 v[174:177], v149 offset:3072
	s_add_u32 s62, s66, s8
	s_addc_u32 s63, s67, s9
	s_mov_b32 m0, s79
	v_lshl_add_u64 v[238:239], s[62:63], 0, v[136:137]
	ds_read_b128 v[178:181], v148 offset:32768
	ds_read_b128 v[182:185], v148 offset:33792
	ds_read_b128 v[186:189], v148 offset:34816
	ds_read_b128 v[190:193], v148 offset:35840
	ds_read_b128 v[194:197], v148 offset:36864
	ds_read_b128 v[198:201], v148 offset:37888
	ds_read_b128 v[202:205], v148 offset:38912
	ds_read_b128 v[214:217], v148 offset:39936
	global_load_lds_dwordx4 v[238:239], off
	v_lshl_add_u64 v[238:239], s[62:63], 0, v[132:133]
	s_mov_b32 m0, s90
	s_nop 0
	global_load_lds_dwordx4 v[238:239], off
	s_waitcnt vmcnt(8)
	s_cmp_lg_u64 s[18:19], 0
	s_cbranch_scc1 .Lrw_g2k
	s_waitcnt lgkmcnt(0)

.Lrw_g3k:
	s_barrier
	s_setprio 1
	s_waitcnt lgkmcnt(0)
	v_mfma_f32_16x16x32_bf16 v[62:65], v[142:145], v[178:181], v[62:65]
	v_mfma_f32_16x16x32_bf16 v[54:57], v[154:157], v[178:181], v[54:57]
	v_mfma_f32_16x16x32_bf16 v[46:49], v[142:145], v[186:189], v[46:49]
	v_mfma_f32_16x16x32_bf16 v[38:41], v[154:157], v[186:189], v[38:41]
	v_mfma_f32_16x16x32_bf16 v[30:33], v[142:145], v[194:197], v[30:33]
	v_mfma_f32_16x16x32_bf16 v[22:25], v[154:157], v[194:197], v[22:25]
	v_mfma_f32_16x16x32_bf16 v[14:17], v[142:145], v[202:205], v[14:17]
	v_mfma_f32_16x16x32_bf16 v[6:9], v[154:157], v[202:205], v[6:9]
	v_mfma_f32_16x16x32_bf16 v[62:65], v[150:153], v[182:185], v[62:65]
	v_mfma_f32_16x16x32_bf16 v[54:57], v[158:161], v[182:185], v[54:57]
	v_mfma_f32_16x16x32_bf16 v[46:49], v[150:153], v[190:193], v[46:49]
	v_mfma_f32_16x16x32_bf16 v[38:41], v[158:161], v[190:193], v[38:41]
	v_mfma_f32_16x16x32_bf16 v[30:33], v[150:153], v[198:201], v[30:33]
	v_mfma_f32_16x16x32_bf16 v[22:25], v[158:161], v[198:201], v[22:25]
	v_mfma_f32_16x16x32_bf16 v[14:17], v[150:153], v[214:217], v[14:17]
	v_mfma_f32_16x16x32_bf16 v[6:9], v[158:161], v[214:217], v[6:9]
	s_setprio 0
	s_setprio 1
	v_mfma_f32_16x16x32_bf16 v[58:61], v[162:165], v[178:181], v[58:61]
	v_mfma_f32_16x16x32_bf16 v[50:53], v[170:173], v[178:181], v[50:53]
	v_mfma_f32_16x16x32_bf16 v[42:45], v[162:165], v[186:189], v[42:45]
	v_mfma_f32_16x16x32_bf16 v[34:37], v[170:173], v[186:189], v[34:37]
	v_mfma_f32_16x16x32_bf16 v[26:29], v[162:165], v[194:197], v[26:29]
	v_mfma_f32_16x16x32_bf16 v[18:21], v[170:173], v[194:197], v[18:21]
	v_mfma_f32_16x16x32_bf16 v[10:13], v[162:165], v[202:205], v[10:13]
	v_mfma_f32_16x16x32_bf16 v[2:5], v[170:173], v[202:205], v[2:5]
	v_mfma_f32_16x16x32_bf16 v[58:61], v[166:169], v[182:185], v[58:61]
	v_mfma_f32_16x16x32_bf16 v[50:53], v[174:177], v[182:185], v[50:53]
	v_mfma_f32_16x16x32_bf16 v[42:45], v[166:169], v[190:193], v[42:45]
	v_mfma_f32_16x16x32_bf16 v[34:37], v[174:177], v[190:193], v[34:37]
	v_mfma_f32_16x16x32_bf16 v[26:29], v[166:169], v[198:201], v[26:29]
	v_mfma_f32_16x16x32_bf16 v[18:21], v[174:177], v[198:201], v[18:21]
	v_mfma_f32_16x16x32_bf16 v[10:13], v[166:169], v[214:217], v[10:13]
	v_mfma_f32_16x16x32_bf16 v[2:5], v[174:177], v[214:217], v[2:5]
	s_setprio 0
	s_barrier
	s_add_u32 s22, s22, 0x100
	s_addc_u32 s23, s23, 0
	s_add_u32 vcc_lo, vcc_lo, 0x100
	s_addc_u32 vcc_hi, vcc_hi, 0
	s_cmp_ge_i32 s88, s52
	s_mov_b32 s66, s88
	s_cbranch_scc0 .LBB0_287

.Lzgo_2:
	s_add_u32 s20, s20, 0x80
	s_addc_u32 s21, s21, 0
	s_add_u32 vcc_lo, s22, 0x100
	s_addc_u32 vcc_hi, s23, 0
	s_mov_b32 s22, 0
	s_add_i32 s88, s22, 2
	s_add_u32 s31, s20, 0x80
	s_addc_u32 s23, s21, 0
	s_add_i32 s89, 0, 0x10000
	s_cmp_eq_u32 s90, s22
	s_cselect_b32 s23, s3, s23
	s_cselect_b32 s22, s2, s31
	v_add_u32_e32 v146, s89, v148
	s_cselect_b32 s63, s19, vcc_hi
	s_cselect_b32 s62, s18, vcc_lo
	s_add_i32 s31, 0, 0x14000
	ds_read_b128 v[138:141], v146
	ds_read_b128 v[142:145], v146 offset:1024
	ds_read_b128 v[152:155], v146 offset:2048
	ds_read_b128 v[156:159], v146 offset:3072
	v_add_u32_e32 v146, s31, v148
	ds_read_b128 v[160:163], v146
	ds_read_b128 v[164:167], v146 offset:1024
	ds_read_b128 v[168:171], v146 offset:2048
	ds_read_b128 v[172:175], v146 offset:3072
	v_lshl_add_u64 v[146:147], s[20:21], 0, v[134:135]
	s_add_i32 m0, s67, 0xc000
	ds_read_b128 v[176:179], v150
	ds_read_b128 v[180:183], v150 offset:1024
	ds_read_b128 v[184:187], v150 offset:2048
	ds_read_b128 v[188:191], v150 offset:3072
	ds_read_b128 v[192:195], v150 offset:4096
	ds_read_b128 v[196:199], v150 offset:5120
	ds_read_b128 v[200:203], v150 offset:6144
	ds_read_b128 v[214:217], v150 offset:7168
	global_load_lds_dwordx4 v[146:147], off
	v_lshl_add_u64 v[146:147], s[20:21], 0, v[136:137]
	s_add_i32 m0, s67, 0xe000
	s_nop 0
	global_load_lds_dwordx4 v[146:147], off
	s_waitcnt vmcnt(8)
	s_cmp_lg_u64 s[16:17], 0
	s_cbranch_scc1 .Lrwp_d0k
	s_waitcnt lgkmcnt(0)
.Lrwp_d0k:
	s_barrier
	s_setprio 1
	s_waitcnt lgkmcnt(0)
	v_mfma_f32_16x16x32_bf16 v[126:129], v[138:141], v[176:179], 0
	v_mfma_f32_16x16x32_bf16 v[94:97], v[152:155], v[176:179], 0
	v_mfma_f32_16x16x32_bf16 v[122:125], v[138:141], v[184:187], 0
	v_mfma_f32_16x16x32_bf16 v[90:93], v[152:155], v[184:187], 0
	v_mfma_f32_16x16x32_bf16 v[118:121], v[138:141], v[192:195], 0
	v_mfma_f32_16x16x32_bf16 v[86:89], v[152:155], v[192:195], 0
	v_mfma_f32_16x16x32_bf16 v[114:117], v[138:141], v[200:203], 0
	v_mfma_f32_16x16x32_bf16 v[82:85], v[152:155], v[200:203], 0
	v_mfma_f32_16x16x32_bf16 v[126:129], v[142:145], v[180:183], v[126:129]
	v_mfma_f32_16x16x32_bf16 v[94:97], v[156:159], v[180:183], v[94:97]
	v_mfma_f32_16x16x32_bf16 v[122:125], v[142:145], v[188:191], v[122:125]
	v_mfma_f32_16x16x32_bf16 v[90:93], v[156:159], v[188:191], v[90:93]
	v_mfma_f32_16x16x32_bf16 v[118:121], v[142:145], v[196:199], v[118:121]
	v_mfma_f32_16x16x32_bf16 v[86:89], v[156:159], v[196:199], v[86:89]
	v_mfma_f32_16x16x32_bf16 v[114:117], v[142:145], v[214:217], v[114:117]
	v_mfma_f32_16x16x32_bf16 v[82:85], v[156:159], v[214:217], v[82:85]
	s_setprio 0
	s_setprio 1
	v_mfma_f32_16x16x32_bf16 v[62:65], v[160:163], v[176:179], 0
	v_mfma_f32_16x16x32_bf16 v[30:33], v[168:171], v[176:179], 0
	v_mfma_f32_16x16x32_bf16 v[58:61], v[160:163], v[184:187], 0
	v_mfma_f32_16x16x32_bf16 v[26:29], v[168:171], v[184:187], 0
	v_mfma_f32_16x16x32_bf16 v[54:57], v[160:163], v[192:195], 0
	v_mfma_f32_16x16x32_bf16 v[22:25], v[168:171], v[192:195], 0
	v_mfma_f32_16x16x32_bf16 v[50:53], v[160:163], v[200:203], 0
	v_mfma_f32_16x16x32_bf16 v[18:21], v[168:171], v[200:203], 0
	v_mfma_f32_16x16x32_bf16 v[62:65], v[164:167], v[180:183], v[62:65]
	v_mfma_f32_16x16x32_bf16 v[30:33], v[172:175], v[180:183], v[30:33]
	v_mfma_f32_16x16x32_bf16 v[58:61], v[164:167], v[188:191], v[58:61]
	v_mfma_f32_16x16x32_bf16 v[26:29], v[172:175], v[188:191], v[26:29]
	v_mfma_f32_16x16x32_bf16 v[54:57], v[164:167], v[196:199], v[54:57]
	v_mfma_f32_16x16x32_bf16 v[22:25], v[172:175], v[196:199], v[22:25]
	v_mfma_f32_16x16x32_bf16 v[50:53], v[164:167], v[214:217], v[50:53]
	v_mfma_f32_16x16x32_bf16 v[18:21], v[172:175], v[214:217], v[18:21]
	s_setprio 0
	s_barrier
	s_add_i32 s89, s89, s56
	v_lshl_add_u64 v[146:147], s[62:63], 0, v[132:133]
	s_mov_b32 m0, s89
	ds_read_b128 v[176:179], v150 offset:16384
	ds_read_b128 v[180:183], v150 offset:17408
	ds_read_b128 v[184:187], v150 offset:18432
	ds_read_b128 v[188:191], v150 offset:19456
	ds_read_b128 v[192:195], v150 offset:20480
	ds_read_b128 v[196:199], v150 offset:21504
	ds_read_b128 v[200:203], v150 offset:22528
	ds_read_b128 v[214:217], v150 offset:23552
	global_load_lds_dwordx4 v[146:147], off
	s_add_i32 m0, s89, 0x2000
	v_lshl_add_u64 v[204:205], s[62:63], 0, v[130:131]
	s_add_u32 s62, s62, s8
	s_addc_u32 s63, s63, s9
	s_add_i32 s31, s31, s56
	global_load_lds_dwordx4 v[204:205], off
	v_lshl_add_u64 v[218:219], s[62:63], 0, v[132:133]
	s_mov_b32 m0, s31
	v_lshl_add_u64 v[220:221], s[62:63], 0, v[130:131]
	global_load_lds_dwordx4 v[218:219], off
	s_add_i32 m0, s31, 0x2000
	v_lshl_add_u64 v[222:223], s[22:23], 0, v[132:133]
	global_load_lds_dwordx4 v[220:221], off
	s_mov_b32 m0, s67
	v_lshl_add_u64 v[224:225], s[22:23], 0, v[130:131]
	global_load_lds_dwordx4 v[222:223], off
	s_mov_b32 m0, s72
	s_nop 0
	global_load_lds_dwordx4 v[224:225], off
	s_waitcnt vmcnt(8)
	s_cmp_lg_u64 s[16:17], 0
	s_cbranch_scc1 .Lrwp_d1k
	s_waitcnt lgkmcnt(0)
.Lrwp_d1k:
	s_barrier
	s_setprio 1
	s_waitcnt lgkmcnt(0)
	v_mfma_f32_16x16x32_bf16 v[110:113], v[138:141], v[176:179], 0
	v_mfma_f32_16x16x32_bf16 v[78:81], v[152:155], v[176:179], 0
	v_mfma_f32_16x16x32_bf16 v[106:109], v[138:141], v[184:187], 0
	v_mfma_f32_16x16x32_bf16 v[74:77], v[152:155], v[184:187], 0
	v_mfma_f32_16x16x32_bf16 v[102:105], v[138:141], v[192:195], 0
	v_mfma_f32_16x16x32_bf16 v[70:73], v[152:155], v[192:195], 0
	v_mfma_f32_16x16x32_bf16 v[98:101], v[138:141], v[200:203], 0
	v_mfma_f32_16x16x32_bf16 v[66:69], v[152:155], v[200:203], 0
	v_mfma_f32_16x16x32_bf16 v[110:113], v[142:145], v[180:183], v[110:113]
	v_mfma_f32_16x16x32_bf16 v[78:81], v[156:159], v[180:183], v[78:81]
	v_mfma_f32_16x16x32_bf16 v[106:109], v[142:145], v[188:191], v[106:109]
	v_mfma_f32_16x16x32_bf16 v[74:77], v[156:159], v[188:191], v[74:77]
	v_mfma_f32_16x16x32_bf16 v[102:105], v[142:145], v[196:199], v[102:105]
	v_mfma_f32_16x16x32_bf16 v[70:73], v[156:159], v[196:199], v[70:73]
	v_mfma_f32_16x16x32_bf16 v[98:101], v[142:145], v[214:217], v[98:101]
	v_mfma_f32_16x16x32_bf16 v[66:69], v[156:159], v[214:217], v[66:69]
	s_setprio 0
	s_setprio 1
	v_mfma_f32_16x16x32_bf16 v[46:49], v[160:163], v[176:179], 0
	v_mfma_f32_16x16x32_bf16 v[14:17], v[168:171], v[176:179], 0
	v_mfma_f32_16x16x32_bf16 v[42:45], v[160:163], v[184:187], 0
	v_mfma_f32_16x16x32_bf16 v[10:13], v[168:171], v[184:187], 0
	v_mfma_f32_16x16x32_bf16 v[38:41], v[160:163], v[192:195], 0
	v_mfma_f32_16x16x32_bf16 v[6:9], v[168:171], v[192:195], 0
	v_mfma_f32_16x16x32_bf16 v[34:37], v[160:163], v[200:203], 0
	v_mfma_f32_16x16x32_bf16 v[2:5], v[168:171], v[200:203], 0
	v_mfma_f32_16x16x32_bf16 v[46:49], v[164:167], v[180:183], v[46:49]
	v_mfma_f32_16x16x32_bf16 v[14:17], v[172:175], v[180:183], v[14:17]
	v_mfma_f32_16x16x32_bf16 v[42:45], v[164:167], v[188:191], v[42:45]
	v_mfma_f32_16x16x32_bf16 v[10:13], v[172:175], v[188:191], v[10:13]
	v_mfma_f32_16x16x32_bf16 v[38:41], v[164:167], v[196:199], v[38:41]
	v_mfma_f32_16x16x32_bf16 v[6:9], v[172:175], v[196:199], v[6:9]
	v_mfma_f32_16x16x32_bf16 v[34:37], v[164:167], v[214:217], v[34:37]
	v_mfma_f32_16x16x32_bf16 v[2:5], v[172:175], v[214:217], v[2:5]
	s_setprio 0
	s_barrier
	s_add_i32 s31, 0, 0x18000
	v_add_u32_e32 v151, s31, v148
	s_add_i32 s62, 0, 0x1c000
	ds_read_b128 v[138:141], v151
	ds_read_b128 v[142:145], v151 offset:1024
	ds_read_b128 v[152:155], v151 offset:2048
	ds_read_b128 v[156:159], v151 offset:3072
	v_add_u32_e32 v151, s62, v148
	ds_read_b128 v[160:163], v151
	ds_read_b128 v[164:167], v151 offset:1024
	ds_read_b128 v[168:171], v151 offset:2048
	ds_read_b128 v[172:175], v151 offset:3072
	s_add_u32 s22, s22, s8
	s_addc_u32 s23, s23, s9
	s_mov_b32 m0, s73
	v_lshl_add_u64 v[226:227], s[22:23], 0, v[132:133]
	ds_read_b128 v[176:179], v150 offset:32768
	ds_read_b128 v[180:183], v150 offset:33792
	ds_read_b128 v[184:187], v150 offset:34816
	ds_read_b128 v[188:191], v150 offset:35840
	ds_read_b128 v[192:195], v150 offset:36864
	ds_read_b128 v[196:199], v150 offset:37888
	ds_read_b128 v[200:203], v150 offset:38912
	ds_read_b128 v[214:217], v150 offset:39936
	global_load_lds_dwordx4 v[226:227], off
	v_lshl_add_u64 v[226:227], s[22:23], 0, v[130:131]
	s_mov_b32 m0, s74
	s_nop 0
	global_load_lds_dwordx4 v[226:227], off
	s_waitcnt vmcnt(8)
	s_cmp_lg_u64 s[16:17], 0
	s_cbranch_scc1 .Lrwp_d2k
	s_waitcnt lgkmcnt(0)
.Lrwp_d2k:
	s_barrier
	s_setprio 1
	s_waitcnt lgkmcnt(0)
	v_mfma_f32_16x16x32_bf16 v[126:129], v[138:141], v[176:179], v[126:129]
	v_mfma_f32_16x16x32_bf16 v[94:97], v[152:155], v[176:179], v[94:97]
	v_mfma_f32_16x16x32_bf16 v[122:125], v[138:141], v[184:187], v[122:125]
	v_mfma_f32_16x16x32_bf16 v[90:93], v[152:155], v[184:187], v[90:93]
	v_mfma_f32_16x16x32_bf16 v[118:121], v[138:141], v[192:195], v[118:121]
	v_mfma_f32_16x16x32_bf16 v[86:89], v[152:155], v[192:195], v[86:89]
	v_mfma_f32_16x16x32_bf16 v[114:117], v[138:141], v[200:203], v[114:117]
	v_mfma_f32_16x16x32_bf16 v[82:85], v[152:155], v[200:203], v[82:85]
	v_mfma_f32_16x16x32_bf16 v[126:129], v[142:145], v[180:183], v[126:129]
	v_mfma_f32_16x16x32_bf16 v[94:97], v[156:159], v[180:183], v[94:97]
	v_mfma_f32_16x16x32_bf16 v[122:125], v[142:145], v[188:191], v[122:125]
	v_mfma_f32_16x16x32_bf16 v[90:93], v[156:159], v[188:191], v[90:93]
	v_mfma_f32_16x16x32_bf16 v[118:121], v[142:145], v[196:199], v[118:121]
	v_mfma_f32_16x16x32_bf16 v[86:89], v[156:159], v[196:199], v[86:89]
	v_mfma_f32_16x16x32_bf16 v[114:117], v[142:145], v[214:217], v[114:117]
	v_mfma_f32_16x16x32_bf16 v[82:85], v[156:159], v[214:217], v[82:85]
	s_setprio 0
	s_setprio 1
	v_mfma_f32_16x16x32_bf16 v[62:65], v[160:163], v[176:179], v[62:65]
	v_mfma_f32_16x16x32_bf16 v[30:33], v[168:171], v[176:179], v[30:33]
	v_mfma_f32_16x16x32_bf16 v[58:61], v[160:163], v[184:187], v[58:61]
	v_mfma_f32_16x16x32_bf16 v[26:29], v[168:171], v[184:187], v[26:29]
	v_mfma_f32_16x16x32_bf16 v[54:57], v[160:163], v[192:195], v[54:57]
	v_mfma_f32_16x16x32_bf16 v[22:25], v[168:171], v[192:195], v[22:25]
	v_mfma_f32_16x16x32_bf16 v[50:53], v[160:163], v[200:203], v[50:53]
	v_mfma_f32_16x16x32_bf16 v[18:21], v[168:171], v[200:203], v[18:21]
	v_mfma_f32_16x16x32_bf16 v[62:65], v[164:167], v[180:183], v[62:65]
	v_mfma_f32_16x16x32_bf16 v[30:33], v[172:175], v[180:183], v[30:33]
	v_mfma_f32_16x16x32_bf16 v[58:61], v[164:167], v[188:191], v[58:61]
	v_mfma_f32_16x16x32_bf16 v[26:29], v[172:175], v[188:191], v[26:29]
	v_mfma_f32_16x16x32_bf16 v[54:57], v[164:167], v[196:199], v[54:57]
	v_mfma_f32_16x16x32_bf16 v[22:25], v[172:175], v[196:199], v[22:25]
	v_mfma_f32_16x16x32_bf16 v[50:53], v[164:167], v[214:217], v[50:53]
	v_mfma_f32_16x16x32_bf16 v[18:21], v[172:175], v[214:217], v[18:21]
	s_setprio 0
	s_barrier
	s_add_i32 s22, s31, s56
	v_lshl_add_u64 v[146:147], v[146:147], 0, s[60:61]
	s_mov_b32 m0, s22
	ds_read_b128 v[176:179], v150 offset:49152
	ds_read_b128 v[180:183], v150 offset:50176
	ds_read_b128 v[184:187], v150 offset:51200
	ds_read_b128 v[188:191], v150 offset:52224
	ds_read_b128 v[192:195], v150 offset:53248
	ds_read_b128 v[196:199], v150 offset:54272
	ds_read_b128 v[200:203], v150 offset:55296
	ds_read_b128 v[214:217], v150 offset:56320
	global_load_lds_dwordx4 v[146:147], off
	v_lshl_add_u64 v[146:147], v[204:205], 0, s[60:61]
	s_add_i32 m0, s22, 0x2000
	s_add_i32 s22, s62, s56
	global_load_lds_dwordx4 v[146:147], off
	v_lshl_add_u64 v[146:147], v[218:219], 0, s[60:61]
	s_mov_b32 m0, s22
	s_nop 0
	global_load_lds_dwordx4 v[146:147], off
	v_lshl_add_u64 v[146:147], v[220:221], 0, s[60:61]
	s_add_i32 m0, s22, 0x2000
	s_nop 0
	global_load_lds_dwordx4 v[146:147], off
	v_lshl_add_u64 v[146:147], v[222:223], 0, s[60:61]
	s_mov_b32 m0, s77
	s_nop 0
	global_load_lds_dwordx4 v[146:147], off
	v_lshl_add_u64 v[146:147], v[224:225], 0, s[60:61]
	s_mov_b32 m0, s78
	s_nop 0
	global_load_lds_dwordx4 v[146:147], off
	s_waitcnt vmcnt(8)
	s_cmp_lg_u64 s[16:17], 0
	s_cbranch_scc1 .Lrwp_d3k
	s_waitcnt lgkmcnt(0)
.Lrwp_d3k:
	s_barrier
	s_setprio 1
	s_waitcnt lgkmcnt(0)
	v_mfma_f32_16x16x32_bf16 v[110:113], v[138:141], v[176:179], v[110:113]
	v_mfma_f32_16x16x32_bf16 v[78:81], v[152:155], v[176:179], v[78:81]
	v_mfma_f32_16x16x32_bf16 v[106:109], v[138:141], v[184:187], v[106:109]
	v_mfma_f32_16x16x32_bf16 v[74:77], v[152:155], v[184:187], v[74:77]
	v_mfma_f32_16x16x32_bf16 v[102:105], v[138:141], v[192:195], v[102:105]
	v_mfma_f32_16x16x32_bf16 v[70:73], v[152:155], v[192:195], v[70:73]
	v_mfma_f32_16x16x32_bf16 v[98:101], v[138:141], v[200:203], v[98:101]
	v_mfma_f32_16x16x32_bf16 v[66:69], v[152:155], v[200:203], v[66:69]
	v_mfma_f32_16x16x32_bf16 v[110:113], v[142:145], v[180:183], v[110:113]
	v_mfma_f32_16x16x32_bf16 v[78:81], v[156:159], v[180:183], v[78:81]
	v_mfma_f32_16x16x32_bf16 v[106:109], v[142:145], v[188:191], v[106:109]
	v_mfma_f32_16x16x32_bf16 v[74:77], v[156:159], v[188:191], v[74:77]
	v_mfma_f32_16x16x32_bf16 v[102:105], v[142:145], v[196:199], v[102:105]
	v_mfma_f32_16x16x32_bf16 v[70:73], v[156:159], v[196:199], v[70:73]
	v_mfma_f32_16x16x32_bf16 v[98:101], v[142:145], v[214:217], v[98:101]
	v_mfma_f32_16x16x32_bf16 v[66:69], v[156:159], v[214:217], v[66:69]
	s_setprio 0
	s_setprio 1
	v_mfma_f32_16x16x32_bf16 v[46:49], v[160:163], v[176:179], v[46:49]
	v_mfma_f32_16x16x32_bf16 v[14:17], v[168:171], v[176:179], v[14:17]
	v_mfma_f32_16x16x32_bf16 v[42:45], v[160:163], v[184:187], v[42:45]
	v_mfma_f32_16x16x32_bf16 v[10:13], v[168:171], v[184:187], v[10:13]
	v_mfma_f32_16x16x32_bf16 v[38:41], v[160:163], v[192:195], v[38:41]
	v_mfma_f32_16x16x32_bf16 v[6:9], v[168:171], v[192:195], v[6:9]
	v_mfma_f32_16x16x32_bf16 v[34:37], v[160:163], v[200:203], v[34:37]
	v_mfma_f32_16x16x32_bf16 v[2:5], v[168:171], v[200:203], v[2:5]
	v_mfma_f32_16x16x32_bf16 v[46:49], v[164:167], v[180:183], v[46:49]
	v_mfma_f32_16x16x32_bf16 v[14:17], v[172:175], v[180:183], v[14:17]
	v_mfma_f32_16x16x32_bf16 v[42:45], v[164:167], v[188:191], v[42:45]
	v_mfma_f32_16x16x32_bf16 v[10:13], v[172:175], v[188:191], v[10:13]
	v_mfma_f32_16x16x32_bf16 v[38:41], v[164:167], v[196:199], v[38:41]
	v_mfma_f32_16x16x32_bf16 v[6:9], v[172:175], v[196:199], v[6:9]
	v_mfma_f32_16x16x32_bf16 v[34:37], v[164:167], v[214:217], v[34:37]
	v_mfma_f32_16x16x32_bf16 v[2:5], v[172:175], v[214:217], v[2:5]
	s_setprio 0
	s_barrier
	s_add_u32 s20, s20, 0x100
	s_addc_u32 s21, s21, 0
	s_add_u32 vcc_lo, vcc_lo, 0x100
	s_addc_u32 vcc_hi, vcc_hi, 0
	s_cmp_ge_i32 s88, s79
	s_mov_b32 s22, s88
	s_cbranch_scc1 .LBB0_361
.LBB0_360:
	s_add_i32 s88, s22, 2
	s_add_u32 s31, s20, 0x80
	s_addc_u32 s23, s21, 0
	s_add_i32 s89, 0, 0x10000
	s_cmp_eq_u32 s90, s22
	s_cselect_b32 s23, s3, s23
	s_cselect_b32 s22, s2, s31
	v_add_u32_e32 v146, s89, v148
	s_cselect_b32 s63, s19, vcc_hi
	s_cselect_b32 s62, s18, vcc_lo
	s_add_i32 s31, 0, 0x14000
	ds_read_b128 v[138:141], v146
	ds_read_b128 v[142:145], v146 offset:1024
	ds_read_b128 v[152:155], v146 offset:2048
	ds_read_b128 v[156:159], v146 offset:3072
	v_add_u32_e32 v146, s31, v148
	ds_read_b128 v[160:163], v146
	ds_read_b128 v[164:167], v146 offset:1024
	ds_read_b128 v[168:171], v146 offset:2048
	ds_read_b128 v[172:175], v146 offset:3072
	v_lshl_add_u64 v[146:147], s[20:21], 0, v[134:135]
	s_add_i32 m0, s67, 0xc000
	ds_read_b128 v[176:179], v150
	ds_read_b128 v[180:183], v150 offset:1024
	ds_read_b128 v[184:187], v150 offset:2048
	ds_read_b128 v[188:191], v150 offset:3072
	ds_read_b128 v[192:195], v150 offset:4096
	ds_read_b128 v[196:199], v150 offset:5120
	ds_read_b128 v[200:203], v150 offset:6144
	ds_read_b128 v[214:217], v150 offset:7168
	global_load_lds_dwordx4 v[146:147], off
	v_lshl_add_u64 v[146:147], s[20:21], 0, v[136:137]
	s_add_i32 m0, s67, 0xe000
	s_nop 0
	global_load_lds_dwordx4 v[146:147], off
	s_waitcnt vmcnt(8)
	s_cmp_lg_u64 s[16:17], 0
	s_cbranch_scc1 .Lrw_d0k
	s_waitcnt lgkmcnt(0)
.Lrw_d0k:
	s_barrier
	s_setprio 1
	s_waitcnt lgkmcnt(0)
	v_mfma_f32_16x16x32_bf16 v[126:129], v[138:141], v[176:179], v[126:129]
	v_mfma_f32_16x16x32_bf16 v[94:97], v[152:155], v[176:179], v[94:97]
	v_mfma_f32_16x16x32_bf16 v[122:125], v[138:141], v[184:187], v[122:125]
	v_mfma_f32_16x16x32_bf16 v[90:93], v[152:155], v[184:187], v[90:93]
	v_mfma_f32_16x16x32_bf16 v[118:121], v[138:141], v[192:195], v[118:121]
	v_mfma_f32_16x16x32_bf16 v[86:89], v[152:155], v[192:195], v[86:89]
	v_mfma_f32_16x16x32_bf16 v[114:117], v[138:141], v[200:203], v[114:117]
	v_mfma_f32_16x16x32_bf16 v[82:85], v[152:155], v[200:203], v[82:85]
	v_mfma_f32_16x16x32_bf16 v[126:129], v[142:145], v[180:183], v[126:129]
	v_mfma_f32_16x16x32_bf16 v[94:97], v[156:159], v[180:183], v[94:97]
	v_mfma_f32_16x16x32_bf16 v[122:125], v[142:145], v[188:191], v[122:125]
	v_mfma_f32_16x16x32_bf16 v[90:93], v[156:159], v[188:191], v[90:93]
	v_mfma_f32_16x16x32_bf16 v[118:121], v[142:145], v[196:199], v[118:121]
	v_mfma_f32_16x16x32_bf16 v[86:89], v[156:159], v[196:199], v[86:89]
	v_mfma_f32_16x16x32_bf16 v[114:117], v[142:145], v[214:217], v[114:117]
	v_mfma_f32_16x16x32_bf16 v[82:85], v[156:159], v[214:217], v[82:85]
	s_setprio 0
	s_setprio 1
	v_mfma_f32_16x16x32_bf16 v[62:65], v[160:163], v[176:179], v[62:65]
	v_mfma_f32_16x16x32_bf16 v[30:33], v[168:171], v[176:179], v[30:33]
	v_mfma_f32_16x16x32_bf16 v[58:61], v[160:163], v[184:187], v[58:61]
	v_mfma_f32_16x16x32_bf16 v[26:29], v[168:171], v[184:187], v[26:29]
	v_mfma_f32_16x16x32_bf16 v[54:57], v[160:163], v[192:195], v[54:57]
	v_mfma_f32_16x16x32_bf16 v[22:25], v[168:171], v[192:195], v[22:25]
	v_mfma_f32_16x16x32_bf16 v[50:53], v[160:163], v[200:203], v[50:53]
	v_mfma_f32_16x16x32_bf16 v[18:21], v[168:171], v[200:203], v[18:21]
	v_mfma_f32_16x16x32_bf16 v[62:65], v[164:167], v[180:183], v[62:65]
	v_mfma_f32_16x16x32_bf16 v[30:33], v[172:175], v[180:183], v[30:33]
	v_mfma_f32_16x16x32_bf16 v[58:61], v[164:167], v[188:191], v[58:61]
	v_mfma_f32_16x16x32_bf16 v[26:29], v[172:175], v[188:191], v[26:29]
	v_mfma_f32_16x16x32_bf16 v[54:57], v[164:167], v[196:199], v[54:57]
	v_mfma_f32_16x16x32_bf16 v[22:25], v[172:175], v[196:199], v[22:25]
	v_mfma_f32_16x16x32_bf16 v[50:53], v[164:167], v[214:217], v[50:53]
	v_mfma_f32_16x16x32_bf16 v[18:21], v[172:175], v[214:217], v[18:21]
	s_setprio 0
	s_barrier
	s_add_i32 s89, s89, s56
	v_lshl_add_u64 v[146:147], s[62:63], 0, v[132:133]
	s_mov_b32 m0, s89
	ds_read_b128 v[176:179], v150 offset:16384
	ds_read_b128 v[180:183], v150 offset:17408
	ds_read_b128 v[184:187], v150 offset:18432
	ds_read_b128 v[188:191], v150 offset:19456
	ds_read_b128 v[192:195], v150 offset:20480
	ds_read_b128 v[196:199], v150 offset:21504
	ds_read_b128 v[200:203], v150 offset:22528
	ds_read_b128 v[214:217], v150 offset:23552
	global_load_lds_dwordx4 v[146:147], off
	s_add_i32 m0, s89, 0x2000
	v_lshl_add_u64 v[204:205], s[62:63], 0, v[130:131]
	s_add_u32 s62, s62, s8
	s_addc_u32 s63, s63, s9
	s_add_i32 s31, s31, s56
	global_load_lds_dwordx4 v[204:205], off
	v_lshl_add_u64 v[218:219], s[62:63], 0, v[132:133]
	s_mov_b32 m0, s31
	v_lshl_add_u64 v[220:221], s[62:63], 0, v[130:131]
	global_load_lds_dwordx4 v[218:219], off
	s_add_i32 m0, s31, 0x2000
	v_lshl_add_u64 v[222:223], s[22:23], 0, v[132:133]
	global_load_lds_dwordx4 v[220:221], off
	s_mov_b32 m0, s67
	v_lshl_add_u64 v[224:225], s[22:23], 0, v[130:131]
	global_load_lds_dwordx4 v[222:223], off
	s_mov_b32 m0, s72
	s_nop 0
	global_load_lds_dwordx4 v[224:225], off
	s_waitcnt vmcnt(8)
	s_cmp_lg_u64 s[16:17], 0
	s_cbranch_scc1 .Lrw_d1k
	s_waitcnt lgkmcnt(0)
.Lrw_d1k:
	s_barrier
	s_setprio 1
	s_waitcnt lgkmcnt(0)
	v_mfma_f32_16x16x32_bf16 v[110:113], v[138:141], v[176:179], v[110:113]
	v_mfma_f32_16x16x32_bf16 v[78:81], v[152:155], v[176:179], v[78:81]
	v_mfma_f32_16x16x32_bf16 v[106:109], v[138:141], v[184:187], v[106:109]
	v_mfma_f32_16x16x32_bf16 v[74:77], v[152:155], v[184:187], v[74:77]
	v_mfma_f32_16x16x32_bf16 v[102:105], v[138:141], v[192:195], v[102:105]
	v_mfma_f32_16x16x32_bf16 v[70:73], v[152:155], v[192:195], v[70:73]
	v_mfma_f32_16x16x32_bf16 v[98:101], v[138:141], v[200:203], v[98:101]
	v_mfma_f32_16x16x32_bf16 v[66:69], v[152:155], v[200:203], v[66:69]
	v_mfma_f32_16x16x32_bf16 v[110:113], v[142:145], v[180:183], v[110:113]
	v_mfma_f32_16x16x32_bf16 v[78:81], v[156:159], v[180:183], v[78:81]
	v_mfma_f32_16x16x32_bf16 v[106:109], v[142:145], v[188:191], v[106:109]
	v_mfma_f32_16x16x32_bf16 v[74:77], v[156:159], v[188:191], v[74:77]
	v_mfma_f32_16x16x32_bf16 v[102:105], v[142:145], v[196:199], v[102:105]
	v_mfma_f32_16x16x32_bf16 v[70:73], v[156:159], v[196:199], v[70:73]
	v_mfma_f32_16x16x32_bf16 v[98:101], v[142:145], v[214:217], v[98:101]
	v_mfma_f32_16x16x32_bf16 v[66:69], v[156:159], v[214:217], v[66:69]
	s_setprio 0
	s_setprio 1
	v_mfma_f32_16x16x32_bf16 v[46:49], v[160:163], v[176:179], v[46:49]
	v_mfma_f32_16x16x32_bf16 v[14:17], v[168:171], v[176:179], v[14:17]
	v_mfma_f32_16x16x32_bf16 v[42:45], v[160:163], v[184:187], v[42:45]
	v_mfma_f32_16x16x32_bf16 v[10:13], v[168:171], v[184:187], v[10:13]
	v_mfma_f32_16x16x32_bf16 v[38:41], v[160:163], v[192:195], v[38:41]
	v_mfma_f32_16x16x32_bf16 v[6:9], v[168:171], v[192:195], v[6:9]
	v_mfma_f32_16x16x32_bf16 v[34:37], v[160:163], v[200:203], v[34:37]
	v_mfma_f32_16x16x32_bf16 v[2:5], v[168:171], v[200:203], v[2:5]
	v_mfma_f32_16x16x32_bf16 v[46:49], v[164:167], v[180:183], v[46:49]
	v_mfma_f32_16x16x32_bf16 v[14:17], v[172:175], v[180:183], v[14:17]
	v_mfma_f32_16x16x32_bf16 v[42:45], v[164:167], v[188:191], v[42:45]
	v_mfma_f32_16x16x32_bf16 v[10:13], v[172:175], v[188:191], v[10:13]
	v_mfma_f32_16x16x32_bf16 v[38:41], v[164:167], v[196:199], v[38:41]
	v_mfma_f32_16x16x32_bf16 v[6:9], v[172:175], v[196:199], v[6:9]
	v_mfma_f32_16x16x32_bf16 v[34:37], v[164:167], v[214:217], v[34:37]
	v_mfma_f32_16x16x32_bf16 v[2:5], v[172:175], v[214:217], v[2:5]
	s_setprio 0
	s_barrier
	s_add_i32 s31, 0, 0x18000
	v_add_u32_e32 v151, s31, v148
	s_add_i32 s62, 0, 0x1c000
	ds_read_b128 v[138:141], v151
	ds_read_b128 v[142:145], v151 offset:1024
	ds_read_b128 v[152:155], v151 offset:2048
	ds_read_b128 v[156:159], v151 offset:3072
	v_add_u32_e32 v151, s62, v148
	ds_read_b128 v[160:163], v151
	ds_read_b128 v[164:167], v151 offset:1024
	ds_read_b128 v[168:171], v151 offset:2048
	ds_read_b128 v[172:175], v151 offset:3072
	s_add_u32 s22, s22, s8
	s_addc_u32 s23, s23, s9
	s_mov_b32 m0, s73
	v_lshl_add_u64 v[226:227], s[22:23], 0, v[132:133]
	ds_read_b128 v[176:179], v150 offset:32768
	ds_read_b128 v[180:183], v150 offset:33792
	ds_read_b128 v[184:187], v150 offset:34816
	ds_read_b128 v[188:191], v150 offset:35840
	ds_read_b128 v[192:195], v150 offset:36864
	ds_read_b128 v[196:199], v150 offset:37888
	ds_read_b128 v[200:203], v150 offset:38912
	ds_read_b128 v[214:217], v150 offset:39936
	global_load_lds_dwordx4 v[226:227], off
	v_lshl_add_u64 v[226:227], s[22:23], 0, v[130:131]
	s_mov_b32 m0, s74
	s_nop 0
	global_load_lds_dwordx4 v[226:227], off
	s_waitcnt vmcnt(8)
	s_cmp_lg_u64 s[16:17], 0
	s_cbranch_scc1 .Lrw_d2k
	s_waitcnt lgkmcnt(0)

.Lrw_d3k:
	s_barrier
	s_setprio 1
	s_waitcnt lgkmcnt(0)
	v_mfma_f32_16x16x32_bf16 v[110:113], v[138:141], v[176:179], v[110:113]
	v_mfma_f32_16x16x32_bf16 v[78:81], v[152:155], v[176:179], v[78:81]
	v_mfma_f32_16x16x32_bf16 v[106:109], v[138:141], v[184:187], v[106:109]
	v_mfma_f32_16x16x32_bf16 v[74:77], v[152:155], v[184:187], v[74:77]
	v_mfma_f32_16x16x32_bf16 v[102:105], v[138:141], v[192:195], v[102:105]
	v_mfma_f32_16x16x32_bf16 v[70:73], v[152:155], v[192:195], v[70:73]
	v_mfma_f32_16x16x32_bf16 v[98:101], v[138:141], v[200:203], v[98:101]
	v_mfma_f32_16x16x32_bf16 v[66:69], v[152:155], v[200:203], v[66:69]
	v_mfma_f32_16x16x32_bf16 v[110:113], v[142:145], v[180:183], v[110:113]
	v_mfma_f32_16x16x32_bf16 v[78:81], v[156:159], v[180:183], v[78:81]
	v_mfma_f32_16x16x32_bf16 v[106:109], v[142:145], v[188:191], v[106:109]
	v_mfma_f32_16x16x32_bf16 v[74:77], v[156:159], v[188:191], v[74:77]
	v_mfma_f32_16x16x32_bf16 v[102:105], v[142:145], v[196:199], v[102:105]
	v_mfma_f32_16x16x32_bf16 v[70:73], v[156:159], v[196:199], v[70:73]
	v_mfma_f32_16x16x32_bf16 v[98:101], v[142:145], v[214:217], v[98:101]
	v_mfma_f32_16x16x32_bf16 v[66:69], v[156:159], v[214:217], v[66:69]
	s_setprio 0
	s_setprio 1
	v_mfma_f32_16x16x32_bf16 v[46:49], v[160:163], v[176:179], v[46:49]
	v_mfma_f32_16x16x32_bf16 v[14:17], v[168:171], v[176:179], v[14:17]
	v_mfma_f32_16x16x32_bf16 v[42:45], v[160:163], v[184:187], v[42:45]
	v_mfma_f32_16x16x32_bf16 v[10:13], v[168:171], v[184:187], v[10:13]
	v_mfma_f32_16x16x32_bf16 v[38:41], v[160:163], v[192:195], v[38:41]
	v_mfma_f32_16x16x32_bf16 v[6:9], v[168:171], v[192:195], v[6:9]
	v_mfma_f32_16x16x32_bf16 v[34:37], v[160:163], v[200:203], v[34:37]
	v_mfma_f32_16x16x32_bf16 v[2:5], v[168:171], v[200:203], v[2:5]
	v_mfma_f32_16x16x32_bf16 v[46:49], v[164:167], v[180:183], v[46:49]
	v_mfma_f32_16x16x32_bf16 v[14:17], v[172:175], v[180:183], v[14:17]
	v_mfma_f32_16x16x32_bf16 v[42:45], v[164:167], v[188:191], v[42:45]
	v_mfma_f32_16x16x32_bf16 v[10:13], v[172:175], v[188:191], v[10:13]
	v_mfma_f32_16x16x32_bf16 v[38:41], v[164:167], v[196:199], v[38:41]
	v_mfma_f32_16x16x32_bf16 v[6:9], v[172:175], v[196:199], v[6:9]
	v_mfma_f32_16x16x32_bf16 v[34:37], v[164:167], v[214:217], v[34:37]
	v_mfma_f32_16x16x32_bf16 v[2:5], v[172:175], v[214:217], v[2:5]
	s_setprio 0
	s_barrier
	s_add_u32 s20, s20, 0x100
	s_addc_u32 s21, s21, 0
	s_add_u32 vcc_lo, vcc_lo, 0x100
	s_addc_u32 vcc_hi, vcc_hi, 0
	s_cmp_ge_i32 s88, s79
	s_mov_b32 s22, s88
	s_cbranch_scc0 .LBB0_360
